# E22: E20 + P3 stagger (half of the WGs start the in-proj GEMM ~10us late so epilogue store bursts interleave)
# baseline (speedup 1.0000x reference)
.LBB0_462:
	s_load_dwordx2 s[2:3], s[78:79], 0x2a8
	v_writelane_b32 v254, s78, 19
	s_waitcnt lgkmcnt(0)
	s_cmp_lt_i32 s2, 4
	s_cselect_b64 s[96:97], -1, 0
	s_and_b64 s[0:1], s[96:97], s[0:1]
	s_andn2_b64 vcc, exec, s[0:1]
	v_writelane_b32 v254, s79, 20
	s_cbranch_vccnz .LBB0_1657
	s_bitcmp1_b32 s76, 3
	s_cbranch_scc0 .Lmy_stg3_done
	s_sleep 127
	s_sleep 127
	s_sleep 127
.Lmy_stg3_done:
	s_load_dword s30, s[78:79], 0x2b0
	v_readfirstlane_b32 s33, v248
	s_waitcnt lgkmcnt(0)
	v_cvt_f32_u32_e32 v1, s30
	s_sub_i32 s0, 0, s30
	v_rcp_iflag_f32_e32 v1, v1
	s_nop 0
	v_mul_f32_e32 v1, 0x4f7ffffe, v1
	v_cvt_u32_f32_e32 v1, v1
	s_nop 0
	v_readfirstlane_b32 s1, v1
	s_mul_i32 s0, s0, s1
	s_mul_hi_u32 s0, s1, s0
	s_add_i32 s1, s1, s0
	s_mul_hi_u32 s0, s76, s1
	s_mul_i32 s0, s0, s30
	s_sub_i32 s0, s76, s0
	s_sub_i32 s1, s0, s30
	s_cmp_ge_u32 s0, s30
	s_cselect_b32 s0, s1, s0
	s_sub_i32 s1, s0, s30
	s_cmp_ge_u32 s0, s30
	s_cselect_b32 s31, s1, s0
	s_cmpk_lt_i32 s31, 0x660
	s_cselect_b64 s[2:3], -1, 0
	s_cmpk_gt_i32 s31, 0x65f
	s_cbranch_scc1 .LBB0_465
	s_ashr_i32 s0, s31, 31
	s_lshr_b32 s0, s0, 29
	s_add_i32 s0, s31, s0
	s_ashr_i32 s1, s0, 3
	s_and_b32 s0, s0, -8
	s_sub_i32 s0, s31, s0
	s_cmp_lt_i32 s0, 0
	s_movk_i32 s4, 0xcd
	s_cselect_b32 s4, s4, 0xcc
	s_mul_i32 s0, s4, s0
	s_add_i32 s0, s0, s1
	s_mul_hi_i32 s1, s0, 0x2aaaaaab
	s_lshr_b32 s4, s1, 31
	s_ashr_i32 s1, s1, 5
	s_add_i32 s1, s1, s4
	s_lshl_b32 s4, s1, 3
	s_sub_i32 s5, 0x44, s4
	s_min_u32 s5, s5, 8
	s_mulk_i32 s1, 0xc0
	s_sub_i32 s6, s0, s1
	v_cvt_f32_ubyte0_e32 v2, s5
	v_cvt_f32_i32_e32 v1, s6
	v_rcp_iflag_f32_e32 v3, v2
	s_ashr_i32 s0, s6, 30
	s_or_b32 s7, s0, 1
	v_mul_f32_e32 v3, v1, v3
	v_trunc_f32_e32 v3, v3
	v_fma_f32 v1, -v3, v2, v1
	v_cvt_i32_f32_e32 v3, v3
	v_cmp_ge_f32_e64 s[0:1], |v1|, v2
	s_and_b64 s[0:1], s[0:1], exec
	s_cselect_b32 s0, s7, 0
	v_readfirstlane_b32 s1, v3
	s_add_i32 s1, s1, s0
	s_sext_i32_i16 s0, s1
	s_mul_i32 s1, s1, s5
	s_sub_i32 s1, s6, s1
	s_sext_i32_i16 s1, s1
	s_add_i32 s6, s4, s1
